# select search: threshold interpolation on v^1.5 scale (fewer count passes in simulation), Illinois factor 0.75
# speedup vs baseline: 1.0052x; 1.0052x over previous
.Lsqa_red:
	v_add_u32_e32 v0, v0, v34
	s_nop 1
	v_add_u32_dpp v0, v0, v0 row_shr:1 row_mask:0xf bank_mask:0xf bound_ctrl:1
	s_nop 1
	v_add_u32_dpp v0, v0, v0 row_shr:2 row_mask:0xf bank_mask:0xf bound_ctrl:1
	s_nop 1
	v_add_u32_dpp v0, v0, v0 row_shr:4 row_mask:0xf bank_mask:0xf bound_ctrl:1
	s_nop 1
	v_add_u32_dpp v0, v0, v0 row_shr:8 row_mask:0xf bank_mask:0xf bound_ctrl:1
	s_nop 1
	v_add_u32_dpp v0, v0, v0 row_bcast:15 row_mask:0xa bank_mask:0xf
	s_nop 1
	v_add_u32_dpp v0, v0, v0 row_bcast:31 row_mask:0xc bank_mask:0xf
	s_nop 0
	v_readlane_b32 s24, v0, 63
	s_cmp_eq_u32 s21, 2
	s_cbranch_scc1 .Lsqa_st2
	s_cmp_eq_u32 s21, 1
	s_cbranch_scc1 .Lsqa_st1
	s_cmpk_eq_i32 s24, 0x100
	s_cbranch_scc1 .Lsqa_exact
	s_cmpk_gt_i32 s24, 0x100
	s_cbranch_scc0 .Lsqa_s0lt
	s_mov_b32 s13, 0x80000001
	s_add_i32 s12, s19, 1
	s_mov_b32 s15, 0
	v_cvt_f32_u32_e32 v35, s24
	v_log_f32_e32 v35, v35
	v_mov_b32_e32 v36, 0x41200b88
	v_add_f32_e32 v35, 0xc1000b88, v35
	s_and_b32 s26, s12, 0x7fffffff
	s_bfe_u32 s27, s26, 0x80017
	s_sub_u32 s27, s27, 0x43
	s_cmp_lt_u32 s27, 0x79
	s_cselect_b32 s101, 1, 0
	v_sqrt_f32_e32 v193, s26
	v_mov_b32_e32 v192, 0
	v_mul_f32_e32 v193, s26, v193
	s_mov_b32 s22, 0
	s_mov_b32 s23, 0
	s_mov_b32 s21, 2
	s_branch .Lsqa_next

; __device__ __forceinline__ float keyval(unsigned k) { return __uint_as_float((k & 0x80000000u) ? (k ^ 0x80000000u) : ~k); }
; __device__ __forceinline__ unsigned valkey(float f) { const unsigned b = __float_as_uint(f); return b ^ ((unsigned)((int)b >> 31) | 0x80000000u); }
; __device__ __forceinline__ void select_query(const unsigned (&u)[64], unsigned vmax, int q, int b, int lane, unsigned* MASKb) {
;     ...
;                 unsigned vmin = 0xffffffffu;
; #pragma unroll
;                 for (int i = 0; i < 64; ++i) vmin = min(vmin, u[i] - 1u);
;                 lo = ~wave_umax(~vmin) + 1u; Llo = __log2f((float)n) - L256; hi = K0; Lhi = L256 - __log2f(fmaxf((float)c0, 0.5f));
;             }
;         }
;         int it = 0, last = 0;
;         while (!done) {
;             if (hi - lo <= 1u) { T = lo; exact = false; break; }
;             const float vlo = keyval(lo), vhi = keyval(hi);
;             const float frac = (it >= 9 && (it & 1)) ? 0.5f : Llo * __builtin_amdgcn_rcpf(Llo + Lhi);
;             unsigned mid = valkey(vlo + frac * (vhi - vlo));
;             if (mid <= lo) mid = lo + 1u;
;             if (mid >= hi) mid = hi - 1u;
;             mid = __builtin_amdgcn_readfirstlane(mid);
;             const int c = count_ge(u, mid, nblk);
;             if (c == 256) { T = mid; exact = true; break; }
;             if (c > 256) { lo = mid; Llo = __log2f((float)c) - L256; if (last == 1) Lhi *= 0.5f; last = 1; }
;             else { hi = mid; Lhi = L256 - __log2f(fmaxf((float)c, 0.5f)); if (last == 2) Llo *= 0.5f; last = 2; }
.Lsqa_s1lt:
	v_mov_b32_e32 v191, -1
	v_add_u32_e32 v0, -1, v138
	v_min_u32_e32 v191, v191, v0
	v_add_u32_e32 v0, -1, v140
	v_min_u32_e32 v191, v191, v0
	v_add_u32_e32 v0, -1, v139
	v_min_u32_e32 v191, v191, v0
	v_add_u32_e32 v0, -1, v141
	v_min_u32_e32 v191, v191, v0
	v_add_u32_e32 v0, -1, v142
	v_min_u32_e32 v191, v191, v0
	v_add_u32_e32 v0, -1, v146
	v_min_u32_e32 v191, v191, v0
	v_add_u32_e32 v0, -1, v143
	v_min_u32_e32 v191, v191, v0
	v_add_u32_e32 v0, -1, v147
	v_min_u32_e32 v191, v191, v0
	v_add_u32_e32 v0, -1, v144
	v_min_u32_e32 v191, v191, v0
	v_add_u32_e32 v0, -1, v148
	v_min_u32_e32 v191, v191, v0
	v_add_u32_e32 v0, -1, v145
	v_min_u32_e32 v191, v191, v0
	v_add_u32_e32 v0, -1, v149
	v_min_u32_e32 v191, v191, v0
	v_add_u32_e32 v0, -1, v150
	v_min_u32_e32 v191, v191, v0
	v_add_u32_e32 v0, -1, v152
	v_min_u32_e32 v191, v191, v0
	v_add_u32_e32 v0, -1, v151
	v_min_u32_e32 v191, v191, v0
	v_add_u32_e32 v0, -1, v154
	v_min_u32_e32 v191, v191, v0
	v_add_u32_e32 v0, -1, v153
	v_min_u32_e32 v191, v191, v0
	v_add_u32_e32 v0, -1, v156
	v_min_u32_e32 v191, v191, v0
	v_add_u32_e32 v0, -1, v155
	v_min_u32_e32 v191, v191, v0
	v_add_u32_e32 v0, -1, v157
	v_min_u32_e32 v191, v191, v0
	v_add_u32_e32 v0, -1, v158
	v_min_u32_e32 v191, v191, v0
	v_add_u32_e32 v0, -1, v160
	v_min_u32_e32 v191, v191, v0
	v_add_u32_e32 v0, -1, v159
	v_min_u32_e32 v191, v191, v0
	v_add_u32_e32 v0, -1, v161
	v_min_u32_e32 v191, v191, v0
	v_add_u32_e32 v0, -1, v167
	v_min_u32_e32 v191, v191, v0
	v_add_u32_e32 v0, -1, v169
	v_min_u32_e32 v191, v191, v0
	v_add_u32_e32 v0, -1, v168
	v_min_u32_e32 v191, v191, v0
	v_add_u32_e32 v0, -1, v170
	v_min_u32_e32 v191, v191, v0
	v_add_u32_e32 v0, -1, v173
	v_min_u32_e32 v191, v191, v0
	v_add_u32_e32 v0, -1, v174
	v_min_u32_e32 v191, v191, v0
	v_add_u32_e32 v0, -1, v175
	v_min_u32_e32 v191, v191, v0
	v_add_u32_e32 v0, -1, v176
	v_min_u32_e32 v191, v191, v0
	v_add_u32_e32 v0, -1, v76
	v_min_u32_e32 v191, v191, v0
	v_add_u32_e32 v0, -1, v78
	v_min_u32_e32 v191, v191, v0
	v_add_u32_e32 v0, -1, v77
	v_min_u32_e32 v191, v191, v0
	v_add_u32_e32 v0, -1, v79
	v_min_u32_e32 v191, v191, v0
	v_add_u32_e32 v0, -1, v80
	v_min_u32_e32 v191, v191, v0
	v_add_u32_e32 v0, -1, v84
	v_min_u32_e32 v191, v191, v0
	v_add_u32_e32 v0, -1, v81
	v_min_u32_e32 v191, v191, v0
	v_add_u32_e32 v0, -1, v85
	v_min_u32_e32 v191, v191, v0
	v_add_u32_e32 v0, -1, v82
	v_min_u32_e32 v191, v191, v0
	v_add_u32_e32 v0, -1, v86
	v_min_u32_e32 v191, v191, v0
	v_add_u32_e32 v0, -1, v83
	v_min_u32_e32 v191, v191, v0
	v_add_u32_e32 v0, -1, v87
	v_min_u32_e32 v191, v191, v0
	v_add_u32_e32 v0, -1, v89
	v_min_u32_e32 v191, v191, v0
	v_add_u32_e32 v0, -1, v91
	v_min_u32_e32 v191, v191, v0
	v_add_u32_e32 v0, -1, v90
	v_min_u32_e32 v191, v191, v0
	v_add_u32_e32 v0, -1, v93
	v_min_u32_e32 v191, v191, v0
	v_add_u32_e32 v0, -1, v92
	v_min_u32_e32 v191, v191, v0
	v_add_u32_e32 v0, -1, v95
	v_min_u32_e32 v191, v191, v0
	v_add_u32_e32 v0, -1, v94
	v_min_u32_e32 v191, v191, v0
	v_add_u32_e32 v0, -1, v96
	v_min_u32_e32 v191, v191, v0
	v_add_u32_e32 v0, -1, v97
	v_min_u32_e32 v191, v191, v0
	v_add_u32_e32 v0, -1, v172
	v_min_u32_e32 v191, v191, v0
	v_add_u32_e32 v0, -1, v171
	v_min_u32_e32 v191, v191, v0
	v_add_u32_e32 v0, -1, v178
	v_min_u32_e32 v191, v191, v0
	v_add_u32_e32 v0, -1, v180
	v_min_u32_e32 v191, v191, v0
	v_add_u32_e32 v0, -1, v183
	v_min_u32_e32 v191, v191, v0
	v_add_u32_e32 v0, -1, v182
	v_min_u32_e32 v191, v191, v0
	v_add_u32_e32 v0, -1, v184
	v_min_u32_e32 v191, v191, v0
	v_add_u32_e32 v0, -1, v186
	v_min_u32_e32 v191, v191, v0
	v_add_u32_e32 v0, -1, v187
	v_min_u32_e32 v191, v191, v0
	v_add_u32_e32 v0, -1, v188
	v_min_u32_e32 v191, v191, v0
	v_add_u32_e32 v0, -1, v189
	v_min_u32_e32 v191, v191, v0
	v_not_b32_e32 v191, v191
	s_nop 1
	v_max_u32_dpp v191, v191, v191 row_shr:1 row_mask:0xf bank_mask:0xf bound_ctrl:1
	s_nop 1
	v_max_u32_dpp v191, v191, v191 row_shr:2 row_mask:0xf bank_mask:0xf bound_ctrl:1
	s_nop 1
	v_max_u32_dpp v191, v191, v191 row_shr:4 row_mask:0xf bank_mask:0xf bound_ctrl:1
	s_nop 1
	v_max_u32_dpp v191, v191, v191 row_shr:8 row_mask:0xf bank_mask:0xf bound_ctrl:1
	s_nop 1
	v_max_u32_dpp v191, v191, v191 row_bcast:15 row_mask:0xa bank_mask:0xf
	s_nop 1
	v_max_u32_dpp v191, v191, v191 row_bcast:31 row_mask:0xc bank_mask:0xf
	s_nop 0
	v_readlane_b32 s26, v191, 63
	s_sub_i32 s13, 0, s26
	s_mov_b32 s12, 0x80000000
	s_mov_b32 s15, s24
	s_add_i32 s26, s75, 1
	v_cvt_f32_u32_e32 v35, s26
	v_log_f32_e32 v35, v35
	v_cvt_f32_u32_e32 v36, s24
	v_max_f32_e32 v36, 0.5, v36
	v_log_f32_e32 v36, v36
	v_add_f32_e32 v35, 0xc1000b88, v35
	v_sub_f32_e32 v36, 0x41000b88, v36
	s_mov_b32 s101, 0
	s_mov_b32 s22, 0
	s_mov_b32 s23, 0
	s_mov_b32 s21, 2
	s_branch .Lsqa_next
.Lsqa_st2:
	s_cmpk_eq_i32 s24, 0x100
	s_cbranch_scc1 .Lsqa_exact
	s_cmpk_gt_i32 s24, 0x100
	s_cbranch_scc0 .Lsqa_s2lt
	s_mov_b32 s13, s14
	v_mov_b32_e32 v192, v88
	v_cvt_f32_u32_e32 v35, s24
	v_log_f32_e32 v35, v35
	s_cmp_lg_u32 s23, 1
	s_cbranch_scc1 .Lsqa_s2a
	v_mul_f32_e32 v36, 0x3f400000, v36

; __device__ __forceinline__ void select_query(const unsigned (&u)[64], unsigned vmax, int q, int b, int lane, unsigned* MASKb) {
;     ...
;             if (c > 256) { lo = mid; Llo = __log2f((float)c) - L256; if (last == 1) Lhi *= 0.5f; last = 1; }
;             else { hi = mid; Lhi = L256 - __log2f(fmaxf((float)c, 0.5f)); if (last == 2) Llo *= 0.5f; last = 2; }
.Lsqa_s2lt:
	s_mov_b32 s12, s14
	s_mov_b32 s15, s24
	v_mov_b32_e32 v193, v88
	v_cvt_f32_u32_e32 v36, s24
	v_max_f32_e32 v36, 0.5, v36
	v_log_f32_e32 v36, v36
	s_cmp_lg_u32 s23, 2
	s_cbranch_scc1 .Lsqa_s2b
	v_mul_f32_e32 v35, 0x3f400000, v35

; __device__ __forceinline__ float keyval(unsigned k) { return __uint_as_float((k & 0x80000000u) ? (k ^ 0x80000000u) : ~k); }
; __device__ __forceinline__ unsigned valkey(float f) { const unsigned b = __float_as_uint(f); return b ^ ((unsigned)((int)b >> 31) | 0x80000000u); }
; __device__ __forceinline__ void select_query(const unsigned (&u)[64], unsigned vmax, int q, int b, int lane, unsigned* MASKb) {
;     ...
;         while (!done) {
;             if (hi - lo <= 1u) { T = lo; exact = false; break; }
;             const float vlo = keyval(lo), vhi = keyval(hi);
;             const float frac = (it >= 9 && (it & 1)) ? 0.5f : Llo * __builtin_amdgcn_rcpf(Llo + Lhi);
;             unsigned mid = valkey(vlo + frac * (vhi - vlo));
;             if (mid <= lo) mid = lo + 1u;
;             if (mid >= hi) mid = hi - 1u;
;             mid = __builtin_amdgcn_readfirstlane(mid);
.Lsqa_next:
	s_sub_u32 s26, s12, s13
	s_cmp_lt_u32 s26, 2
	s_cbranch_scc1 .Lsqa_collapse
	s_cmp_eq_u32 s101, 0
	s_cbranch_scc1 .Lsqa_lin
	s_cmp_lt_i32 s22, 9
	s_cbranch_scc0 .Lsqa_lin
	v_add_f32_e32 v191, v35, v36
	v_sub_f32_e32 v34, v193, v192
	v_rcp_f32_e32 v191, v191
	s_nop 0
	v_mul_f32_e32 v191, v35, v191
	v_fma_f32 v88, v191, v34, v192
	v_log_f32_e32 v0, v88
	s_nop 0
	v_mul_f32_e32 v0, 0x3f2aaaab, v0
	v_exp_f32_e32 v191, v0
	s_nop 0
	s_branch .Lsqa_key
.Lsqa_lin:
	s_cmp_gt_i32 s13, -1
	s_cselect_b32 s26, -1, 0x80000000
	s_xor_b32 s16, s13, s26
	s_cmp_gt_i32 s12, -1
	s_cselect_b32 s26, -1, 0x80000000
	s_xor_b32 s17, s12, s26
	s_cmp_lt_i32 s22, 9
	s_cbranch_scc1 .Lsqa_interp
	s_bitcmp1_b32 s22, 0
	s_cbranch_scc0 .Lsqa_interp
	v_mov_b32_e32 v191, 0.5
	s_branch .Lsqa_frac

; __device__ __forceinline__ unsigned valkey(float f) { const unsigned b = __float_as_uint(f); return b ^ ((unsigned)((int)b >> 31) | 0x80000000u); }
; __device__ __forceinline__ void select_query(const unsigned (&u)[64], unsigned vmax, int q, int b, int lane, unsigned* MASKb) {
;     ...
;             unsigned mid = valkey(vlo + frac * (vhi - vlo));
;             if (mid <= lo) mid = lo + 1u;
;             if (mid >= hi) mid = hi - 1u;
;             mid = __builtin_amdgcn_readfirstlane(mid);
.Lsqa_key:
	v_ashrrev_i32_e32 v0, 31, v191
	v_bitop3_b32 v191, v0, v191, s38 bitop3:0x36
	s_nop 0
	v_readfirstlane_b32 s14, v191
	s_add_i32 s26, s13, 1
	s_max_u32 s14, s14, s26
	s_add_i32 s26, s12, -1
	s_min_u32 s14, s14, s26
	s_branch .Lsqa_count

; __device__ __forceinline__ int wave_isum(int v) {
;     v += __builtin_amdgcn_update_dpp(0, v, 0x111, 0xf, 0xf, false);
;     v += __builtin_amdgcn_update_dpp(0, v, 0x112, 0xf, 0xf, false);
;     v += __builtin_amdgcn_update_dpp(0, v, 0x114, 0xf, 0xf, false);
;     v += __builtin_amdgcn_update_dpp(0, v, 0x118, 0xf, 0xf, false);
;     v += __builtin_amdgcn_update_dpp(0, v, 0x142, 0xa, 0xf, false);
;     v += __builtin_amdgcn_update_dpp(0, v, 0x143, 0xc, 0xf, false);
;     return __builtin_amdgcn_readlane(v, 63);
; }
; __device__ __forceinline__ void select_query(const unsigned (&u)[64], unsigned vmax, int q, int b, int lane, unsigned* MASKb) {
;     ...
;         const int cpos = count_ge(u, K0 + 1u, nblk);
;         if (cpos == 256) { T = K0 + 1u; exact = true; done = true; }
;         else if (cpos > 256) { lo = K0 + 1u; Llo = __log2f((float)cpos) - L256; hi = kmax + 1u; Lhi = L256 + 1.f; }
.Lsqb_red:
	v_add_u32_e32 v138, v138, v140
	s_nop 1
	v_add_u32_dpp v138, v138, v138 row_shr:1 row_mask:0xf bank_mask:0xf bound_ctrl:1
	s_nop 1
	v_add_u32_dpp v138, v138, v138 row_shr:2 row_mask:0xf bank_mask:0xf bound_ctrl:1
	s_nop 1
	v_add_u32_dpp v138, v138, v138 row_shr:4 row_mask:0xf bank_mask:0xf bound_ctrl:1
	s_nop 1
	v_add_u32_dpp v138, v138, v138 row_shr:8 row_mask:0xf bank_mask:0xf bound_ctrl:1
	s_nop 1
	v_add_u32_dpp v138, v138, v138 row_bcast:15 row_mask:0xa bank_mask:0xf
	s_nop 1
	v_add_u32_dpp v138, v138, v138 row_bcast:31 row_mask:0xc bank_mask:0xf
	s_nop 0
	v_readlane_b32 s24, v138, 63
	s_cmp_eq_u32 s21, 2
	s_cbranch_scc1 .Lsqb_st2
	s_cmp_eq_u32 s21, 1
	s_cbranch_scc1 .Lsqb_st1
	s_cmpk_eq_i32 s24, 0x100
	s_cbranch_scc1 .Lsqb_exact
	s_cmpk_gt_i32 s24, 0x100
	s_cbranch_scc0 .Lsqb_s0lt
	s_mov_b32 s13, 0x80000001
	s_add_i32 s12, s19, 1
	s_mov_b32 s15, 0
	v_cvt_f32_u32_e32 v139, s24
	v_log_f32_e32 v139, v139
	v_mov_b32_e32 v141, 0x41200b88
	v_add_f32_e32 v139, 0xc1000b88, v139
	s_and_b32 s26, s12, 0x7fffffff
	s_bfe_u32 s27, s26, 0x80017
	s_sub_u32 s27, s27, 0x43
	s_cmp_lt_u32 s27, 0x79
	s_cselect_b32 s101, 1, 0
	v_sqrt_f32_e32 v77, s26
	v_mov_b32_e32 v76, 0
	v_mul_f32_e32 v77, s26, v77
	s_mov_b32 s22, 0
	s_mov_b32 s23, 0
	s_mov_b32 s21, 2
	s_branch .Lsqb_next

; __device__ __forceinline__ void select_query(const unsigned (&u)[64], unsigned vmax, int q, int b, int lane, unsigned* MASKb) {
;     ...
;                 unsigned vmin = 0xffffffffu;
; #pragma unroll
;                 for (int i = 0; i < 64; ++i) vmin = min(vmin, u[i] - 1u);
;                 lo = ~wave_umax(~vmin) + 1u; Llo = __log2f((float)n) - L256; hi = K0; Lhi = L256 - __log2f(fmaxf((float)c0, 0.5f));
;     ...
;             const int c = count_ge(u, mid, nblk);
;             if (c == 256) { T = mid; exact = true; break; }
;             if (c > 256) { lo = mid; Llo = __log2f((float)c) - L256; if (last == 1) Lhi *= 0.5f; last = 1; }
.Lsqb_s1lt:
	v_mov_b32_e32 v142, -1
	v_add_u32_e32 v138, -1, v98
	v_min_u32_e32 v142, v142, v138
	v_add_u32_e32 v138, -1, v107
	v_min_u32_e32 v142, v142, v138
	v_add_u32_e32 v138, -1, v99
	v_min_u32_e32 v142, v142, v138
	v_add_u32_e32 v138, -1, v108
	v_min_u32_e32 v142, v142, v138
	v_add_u32_e32 v138, -1, v109
	v_min_u32_e32 v142, v142, v138
	v_add_u32_e32 v138, -1, v113
	v_min_u32_e32 v142, v142, v138
	v_add_u32_e32 v138, -1, v110
	v_min_u32_e32 v142, v142, v138
	v_add_u32_e32 v138, -1, v114
	v_min_u32_e32 v142, v142, v138
	v_add_u32_e32 v138, -1, v111
	v_min_u32_e32 v142, v142, v138
	v_add_u32_e32 v138, -1, v115
	v_min_u32_e32 v142, v142, v138
	v_add_u32_e32 v138, -1, v112
	v_min_u32_e32 v142, v142, v138
	v_add_u32_e32 v138, -1, v116
	v_min_u32_e32 v142, v142, v138
	v_add_u32_e32 v138, -1, v117
	v_min_u32_e32 v142, v142, v138
	v_add_u32_e32 v138, -1, v119
	v_min_u32_e32 v142, v142, v138
	v_add_u32_e32 v138, -1, v118
	v_min_u32_e32 v142, v142, v138
	v_add_u32_e32 v138, -1, v121
	v_min_u32_e32 v142, v142, v138
	v_add_u32_e32 v138, -1, v120
	v_min_u32_e32 v142, v142, v138
	v_add_u32_e32 v138, -1, v123
	v_min_u32_e32 v142, v142, v138
	v_add_u32_e32 v138, -1, v122
	v_min_u32_e32 v142, v142, v138
	v_add_u32_e32 v138, -1, v124
	v_min_u32_e32 v142, v142, v138
	v_add_u32_e32 v138, -1, v125
	v_min_u32_e32 v142, v142, v138
	v_add_u32_e32 v138, -1, v127
	v_min_u32_e32 v142, v142, v138
	v_add_u32_e32 v138, -1, v126
	v_min_u32_e32 v142, v142, v138
	v_add_u32_e32 v138, -1, v128
	v_min_u32_e32 v142, v142, v138
	v_add_u32_e32 v138, -1, v129
	v_min_u32_e32 v142, v142, v138
	v_add_u32_e32 v138, -1, v131
	v_min_u32_e32 v142, v142, v138
	v_add_u32_e32 v138, -1, v130
	v_min_u32_e32 v142, v142, v138
	v_add_u32_e32 v138, -1, v132
	v_min_u32_e32 v142, v142, v138
	v_add_u32_e32 v138, -1, v133
	v_min_u32_e32 v142, v142, v138
	v_add_u32_e32 v138, -1, v134
	v_min_u32_e32 v142, v142, v138
	v_add_u32_e32 v138, -1, v136
	v_min_u32_e32 v142, v142, v138
	v_add_u32_e32 v138, -1, v137
	v_min_u32_e32 v142, v142, v138
	v_add_u32_e32 v138, -1, v46
	v_min_u32_e32 v142, v142, v138
	v_add_u32_e32 v138, -1, v48
	v_min_u32_e32 v142, v142, v138
	v_add_u32_e32 v138, -1, v47
	v_min_u32_e32 v142, v142, v138
	v_add_u32_e32 v138, -1, v49
	v_min_u32_e32 v142, v142, v138
	v_add_u32_e32 v138, -1, v42
	v_min_u32_e32 v142, v142, v138
	v_add_u32_e32 v138, -1, v50
	v_min_u32_e32 v142, v142, v138
	v_add_u32_e32 v138, -1, v43
	v_min_u32_e32 v142, v142, v138
	v_add_u32_e32 v138, -1, v44
	v_min_u32_e32 v142, v142, v138
	v_add_u32_e32 v138, -1, v38
	v_min_u32_e32 v142, v142, v138
	v_add_u32_e32 v138, -1, v45
	v_min_u32_e32 v142, v142, v138
	v_add_u32_e32 v138, -1, v39
	v_min_u32_e32 v142, v142, v138
	v_add_u32_e32 v138, -1, v40
	v_min_u32_e32 v142, v142, v138
	v_add_u32_e32 v138, -1, v41
	v_min_u32_e32 v142, v142, v138
	v_add_u32_e32 v138, -1, v52
	v_min_u32_e32 v142, v142, v138
	v_add_u32_e32 v138, -1, v51
	v_min_u32_e32 v142, v142, v138
	v_add_u32_e32 v138, -1, v54
	v_min_u32_e32 v142, v142, v138
	v_add_u32_e32 v138, -1, v53
	v_min_u32_e32 v142, v142, v138
	v_add_u32_e32 v138, -1, v56
	v_min_u32_e32 v142, v142, v138
	v_add_u32_e32 v138, -1, v55
	v_min_u32_e32 v142, v142, v138
	v_add_u32_e32 v138, -1, v57
	v_min_u32_e32 v142, v142, v138
	v_add_u32_e32 v138, -1, v58
	v_min_u32_e32 v142, v142, v138
	v_add_u32_e32 v138, -1, v60
	v_min_u32_e32 v142, v142, v138
	v_add_u32_e32 v138, -1, v59
	v_min_u32_e32 v142, v142, v138
	v_add_u32_e32 v138, -1, v61
	v_min_u32_e32 v142, v142, v138
	v_add_u32_e32 v138, -1, v62
	v_min_u32_e32 v142, v142, v138
	v_add_u32_e32 v138, -1, v64
	v_min_u32_e32 v142, v142, v138
	v_add_u32_e32 v138, -1, v63
	v_min_u32_e32 v142, v142, v138
	v_add_u32_e32 v138, -1, v65
	v_min_u32_e32 v142, v142, v138
	v_add_u32_e32 v138, -1, v72
	v_min_u32_e32 v142, v142, v138
	v_add_u32_e32 v138, -1, v73
	v_min_u32_e32 v142, v142, v138
	v_add_u32_e32 v138, -1, v74
	v_min_u32_e32 v142, v142, v138
	v_add_u32_e32 v138, -1, v75
	v_min_u32_e32 v142, v142, v138
	v_not_b32_e32 v142, v142
	s_nop 1
	v_max_u32_dpp v142, v142, v142 row_shr:1 row_mask:0xf bank_mask:0xf bound_ctrl:1
	s_nop 1
	v_max_u32_dpp v142, v142, v142 row_shr:2 row_mask:0xf bank_mask:0xf bound_ctrl:1
	s_nop 1
	v_max_u32_dpp v142, v142, v142 row_shr:4 row_mask:0xf bank_mask:0xf bound_ctrl:1
	s_nop 1
	v_max_u32_dpp v142, v142, v142 row_shr:8 row_mask:0xf bank_mask:0xf bound_ctrl:1
	s_nop 1
	v_max_u32_dpp v142, v142, v142 row_bcast:15 row_mask:0xa bank_mask:0xf
	s_nop 1
	v_max_u32_dpp v142, v142, v142 row_bcast:31 row_mask:0xc bank_mask:0xf
	s_nop 0
	v_readlane_b32 s26, v142, 63
	s_sub_i32 s13, 0, s26
	s_mov_b32 s12, 0x80000000
	s_mov_b32 s15, s24
	s_add_i32 s26, s75, 2
	v_cvt_f32_u32_e32 v139, s26
	v_log_f32_e32 v139, v139
	v_cvt_f32_u32_e32 v141, s24
	v_max_f32_e32 v141, 0.5, v141
	v_log_f32_e32 v141, v141
	v_add_f32_e32 v139, 0xc1000b88, v139
	v_sub_f32_e32 v141, 0x41000b88, v141
	s_mov_b32 s101, 0
	s_mov_b32 s22, 0
	s_mov_b32 s23, 0
	s_mov_b32 s21, 2
	s_branch .Lsqb_next
.Lsqb_st2:
	s_cmpk_eq_i32 s24, 0x100
	s_cbranch_scc1 .Lsqb_exact
	s_cmpk_gt_i32 s24, 0x100
	s_cbranch_scc0 .Lsqb_s2lt
	s_mov_b32 s13, s14
	v_mov_b32_e32 v76, v146
	v_cvt_f32_u32_e32 v139, s24
	v_log_f32_e32 v139, v139
	s_cmp_lg_u32 s23, 1
	s_cbranch_scc1 .Lsqb_s2a
	v_mul_f32_e32 v141, 0x3f400000, v141

; __device__ __forceinline__ void select_query(const unsigned (&u)[64], unsigned vmax, int q, int b, int lane, unsigned* MASKb) {
;     ...
;             if (c > 256) { lo = mid; Llo = __log2f((float)c) - L256; if (last == 1) Lhi *= 0.5f; last = 1; }
;             else { hi = mid; Lhi = L256 - __log2f(fmaxf((float)c, 0.5f)); if (last == 2) Llo *= 0.5f; last = 2; }
.Lsqb_s2lt:
	s_mov_b32 s12, s14
	s_mov_b32 s15, s24
	v_mov_b32_e32 v77, v146
	v_cvt_f32_u32_e32 v141, s24
	v_max_f32_e32 v141, 0.5, v141
	v_log_f32_e32 v141, v141
	s_cmp_lg_u32 s23, 2
	s_cbranch_scc1 .Lsqb_s2b
	v_mul_f32_e32 v139, 0x3f400000, v139

; __device__ __forceinline__ float keyval(unsigned k) { return __uint_as_float((k & 0x80000000u) ? (k ^ 0x80000000u) : ~k); }
; __device__ __forceinline__ unsigned valkey(float f) { const unsigned b = __float_as_uint(f); return b ^ ((unsigned)((int)b >> 31) | 0x80000000u); }
; __device__ __forceinline__ void select_query(const unsigned (&u)[64], unsigned vmax, int q, int b, int lane, unsigned* MASKb) {
;     ...
;         while (!done) {
;             if (hi - lo <= 1u) { T = lo; exact = false; break; }
;             const float vlo = keyval(lo), vhi = keyval(hi);
;             const float frac = (it >= 9 && (it & 1)) ? 0.5f : Llo * __builtin_amdgcn_rcpf(Llo + Lhi);
;             unsigned mid = valkey(vlo + frac * (vhi - vlo));
;             if (mid <= lo) mid = lo + 1u;
;             if (mid >= hi) mid = hi - 1u;
.Lsqb_next:
	s_sub_u32 s26, s12, s13
	s_cmp_lt_u32 s26, 2
	s_cbranch_scc1 .Lsqb_collapse
	s_cmp_eq_u32 s101, 0
	s_cbranch_scc1 .Lsqb_lin
	s_cmp_lt_i32 s22, 9
	s_cbranch_scc0 .Lsqb_lin
	v_add_f32_e32 v142, v139, v141
	v_sub_f32_e32 v140, v77, v76
	v_rcp_f32_e32 v142, v142
	s_nop 0
	v_mul_f32_e32 v142, v139, v142
	v_fma_f32 v146, v142, v140, v76
	v_log_f32_e32 v138, v146
	s_nop 0
	v_mul_f32_e32 v138, 0x3f2aaaab, v138
	v_exp_f32_e32 v142, v138
	s_nop 0
	s_branch .Lsqb_key
.Lsqb_lin:
	s_cmp_gt_i32 s13, -1
	s_cselect_b32 s26, -1, 0x80000000
	s_xor_b32 s16, s13, s26
	s_cmp_gt_i32 s12, -1
	s_cselect_b32 s26, -1, 0x80000000
	s_xor_b32 s17, s12, s26
	s_cmp_lt_i32 s22, 9
	s_cbranch_scc1 .Lsqb_interp
	s_bitcmp1_b32 s22, 0
	s_cbranch_scc0 .Lsqb_interp
	v_mov_b32_e32 v142, 0.5
	s_branch .Lsqb_frac

; __device__ __forceinline__ unsigned valkey(float f) { const unsigned b = __float_as_uint(f); return b ^ ((unsigned)((int)b >> 31) | 0x80000000u); }
; __device__ __forceinline__ void select_query(const unsigned (&u)[64], unsigned vmax, int q, int b, int lane, unsigned* MASKb) {
;     ...
;             unsigned mid = valkey(vlo + frac * (vhi - vlo));
;             if (mid <= lo) mid = lo + 1u;
;             if (mid >= hi) mid = hi - 1u;
;             mid = __builtin_amdgcn_readfirstlane(mid);
.Lsqb_key:
	v_ashrrev_i32_e32 v138, 31, v142
	v_bitop3_b32 v142, v138, v142, s38 bitop3:0x36
	s_nop 0
	v_readfirstlane_b32 s14, v142
	s_add_i32 s26, s13, 1
	s_max_u32 s14, s14, s26
	s_add_i32 s26, s12, -1
	s_min_u32 s14, s14, s26
	s_branch .Lsqb_count
